# norm0 pass rewritten by hand: 8 rows per wave with the loads of 4 rows in flight and one batched wave reduction; shift-table row loop prefetches the next weight row
# speedup vs baseline: 1.0016x; 1.0016x over previous
; __device__ __forceinline__ unsigned pk_bf16(float lo, float hi) { return pg8::cvt_pk_bf16(lo, hi); }
; __device__ __forceinline__ void norm0_phase(const Args& a, LAS unsigned char* lds, const int tid) {
;     ...
;         for (int chunk = gw; chunk * 8 < MT; chunk += ngw) {
;             const int b = (chunk * 8) >> 11;
;             f32x4 sc1[4];
; #pragma unroll
;             for (int j = 0; j < 4; ++j) sc1[j] = (*(const f32x4*)(mod + b * MODW + 1024 + 4 * lane + 256 * j) + 1.0f) * gm[j];
; #pragma unroll 2
;             for (int k = 0; k < 8; ++k) {
;                 const int row = chunk * 8 + k;
;                 const float* xr = a.in[0] + (size_t)row * DM + 4 * lane;
;                 f32x4 v[4]; float ss = 0.f;
; #pragma unroll
;                 for (int j = 0; j < 4; ++j) { v[j] = __builtin_nontemporal_load((const f32x4*)(xr + 256 * j)); ss += (v[j][0] * v[j][0] + v[j][1] * v[j][1]) + (v[j][2] * v[j][2] + v[j][3] * v[j][3]); }
;                 ss = wave_sum(ss);
;                 if (lane == 0) *(f32x4*)(rowss + (size_t)row * 4) = (f32x4){ss, 0.f, 0.f, 0.f};
;                 bf16_t* hr = H + (size_t)row * DM + 4 * lane;
; #pragma unroll
;                 for (int j = 0; j < 4; ++j) {
;                     const f32x4 t = v[j] * sc1[j];
;                     u32x2 o; o.x = pk_bf16(t[0], t[1]); o.y = pk_bf16(t[2], t[3]);
;                     *(u32x2*)(hr + 256 * j) = o;
;                 }
;             }
.LBB0_29:
	v_lshrrev_b32_e32 v0, 8, v71
	v_mul_i32_i24_e32 v2, 0x1800, v0
	v_readlane_b32 s6, v249, 13
	s_waitcnt lgkmcnt(0)
	v_ashrrev_i32_e32 v3, 31, v2
	v_readlane_b32 s7, v249, 14
	v_ashrrev_i32_e32 v43, 31, v42
	v_lshlrev_b64 v[48:49], 11, v[42:43]
	v_lshl_add_u64 v[2:3], v[2:3], 2, s[6:7]
	v_lshl_add_u64 v[2:3], v[2:3], 0, v[44:45]
	s_movk_i32 s6, 0x1000
	v_add_co_u32_e32 v20, vcc, s6, v2
	s_mov_b64 s[6:7], 0
	s_nop 0
	v_addc_co_u32_e32 v21, vcc, 0, v3, vcc
	v_lshl_add_u64 v[2:3], v[2:3], 0, s[22:23]
	global_load_dwordx4 v[20:23], v[20:21], off
	s_nop 0
	global_load_dwordx4 v[24:27], v[2:3], off offset:1024
	global_load_dwordx4 v[28:31], v[2:3], off offset:2048
	global_load_dwordx4 v[32:35], v[2:3], off offset:3072
	v_mov_b64_e32 v[2:3], 0x300000
	v_lshl_add_u64 v[46:47], v[42:43], 4, v[2:3]
	v_lshlrev_b64 v[2:3], 12, v[42:43]
	v_lshl_add_u64 v[50:51], v[40:41], 0, v[2:3]
	v_or_b32_e32 v48, v36, v48
	v_mov_b32_e32 v68, v37
	s_waitcnt vmcnt(2)
	v_pk_add_f32 v[24:25], v[24:25], 1.0 op_sel_hi:[1,0]
	v_pk_add_f32 v[2:3], v[22:23], 1.0 op_sel_hi:[1,0]
	v_pk_add_f32 v[20:21], v[20:21], 1.0 op_sel_hi:[1,0]
	v_pk_add_f32 v[22:23], v[26:27], 1.0 op_sel_hi:[1,0]
	s_waitcnt vmcnt(1)
	v_pk_add_f32 v[26:27], v[30:31], 1.0 op_sel_hi:[1,0]
	v_pk_add_f32 v[28:29], v[28:29], 1.0 op_sel_hi:[1,0]
	s_waitcnt vmcnt(0)
	v_pk_add_f32 v[30:31], v[34:35], 1.0 op_sel_hi:[1,0]
	v_pk_add_f32 v[32:33], v[32:33], 1.0 op_sel_hi:[1,0]
	v_pk_mul_f32 v[52:53], v[6:7], v[2:3]
	v_pk_mul_f32 v[54:55], v[4:5], v[20:21]
	v_pk_mul_f32 v[56:57], v[10:11], v[22:23]
	v_pk_mul_f32 v[58:59], v[8:9], v[24:25]
	v_pk_mul_f32 v[60:61], v[14:15], v[26:27]
	v_pk_mul_f32 v[62:63], v[12:13], v[28:29]
	v_pk_mul_f32 v[64:65], v[18:19], v[30:31]
	v_pk_mul_f32 v[66:67], v[16:17], v[32:33]
	v_mov_b32_e32 v150, v50
	v_mov_b32_e32 v151, v51
	global_load_dwordx4 v[72:75], v[150:151], off nt
	global_load_dwordx4 v[76:79], v[150:151], off offset:1024 nt
	global_load_dwordx4 v[80:83], v[150:151], off offset:2048 nt
	global_load_dwordx4 v[84:87], v[150:151], off offset:3072 nt
	v_lshl_add_u64 v[150:151], v[150:151], 0, s[22:23]
	global_load_dwordx4 v[88:91], v[150:151], off nt
	global_load_dwordx4 v[92:95], v[150:151], off offset:1024 nt
	global_load_dwordx4 v[96:99], v[150:151], off offset:2048 nt
	global_load_dwordx4 v[100:103], v[150:151], off offset:3072 nt
	v_lshl_add_u64 v[150:151], v[150:151], 0, s[22:23]
	global_load_dwordx4 v[104:107], v[150:151], off nt
	global_load_dwordx4 v[108:111], v[150:151], off offset:1024 nt
	global_load_dwordx4 v[112:115], v[150:151], off offset:2048 nt
	global_load_dwordx4 v[116:119], v[150:151], off offset:3072 nt
	v_lshl_add_u64 v[150:151], v[150:151], 0, s[22:23]
	global_load_dwordx4 v[132:135], v[150:151], off nt
	global_load_dwordx4 v[136:139], v[150:151], off offset:1024 nt
	global_load_dwordx4 v[140:143], v[150:151], off offset:2048 nt
	global_load_dwordx4 v[144:147], v[150:151], off offset:3072 nt
	v_lshl_add_u64 v[150:151], v[150:151], 0, s[22:23]
	s_mov_b64 s[10:11], 0x3600000
	v_lshl_add_u64 v[168:169], s[46:47], 0, v[48:49]
	v_lshl_add_u64 v[168:169], v[168:169], 0, s[10:11]
	s_waitcnt vmcnt(12)
	v_mul_f32_e32 v0, v73, v73
	v_mul_f32_e32 v2, v75, v75
	v_mul_f32_e32 v3, v77, v77
	v_mul_f32_e32 v43, v79, v79
	v_mul_f32_e32 v69, v81, v81
	v_mul_f32_e32 v128, v83, v83
	v_fmac_f32_e32 v0, v72, v72
	v_fmac_f32_e32 v2, v74, v74
	v_fmac_f32_e32 v3, v76, v76
	v_fmac_f32_e32 v43, v78, v78
	v_mul_f32_e32 v129, v85, v85
	v_mul_f32_e32 v148, v87, v87
	v_fmac_f32_e32 v69, v80, v80
	v_fmac_f32_e32 v128, v82, v82
	v_add_f32_e32 v0, v0, v2
	v_add_f32_e32 v2, v3, v43
	v_fmac_f32_e32 v129, v84, v84
	v_fmac_f32_e32 v148, v86, v86
	v_add_f32_e32 v3, v69, v128
	v_add_f32_e32 v0, v0, v2
	v_add_f32_e32 v0, v0, v3
	v_add_f32_e32 v2, v129, v148
	v_add_f32_e32 v120, v0, v2
	v_pk_mul_f32 v[72:73], v[54:55], v[72:73]
	v_pk_mul_f32 v[74:75], v[52:53], v[74:75]
	v_pk_mul_f32 v[76:77], v[58:59], v[76:77]
	v_pk_mul_f32 v[78:79], v[56:57], v[78:79]
	v_pk_mul_f32 v[80:81], v[62:63], v[80:81]
	v_pk_mul_f32 v[82:83], v[60:61], v[82:83]
	v_pk_mul_f32 v[84:85], v[66:67], v[84:85]
	v_pk_mul_f32 v[86:87], v[64:65], v[86:87]
	v_cvt_pk_bf16_f32 v28, v72, v73
	v_cvt_pk_bf16_f32 v29, v74, v75
	global_store_dwordx2 v[168:169], v[28:29], off
	v_cvt_pk_bf16_f32 v30, v76, v77
	v_cvt_pk_bf16_f32 v31, v78, v79
	global_store_dwordx2 v[168:169], v[30:31], off offset:512
	v_cvt_pk_bf16_f32 v32, v80, v81
	v_cvt_pk_bf16_f32 v33, v82, v83
	global_store_dwordx2 v[168:169], v[32:33], off offset:1024
	v_cvt_pk_bf16_f32 v34, v84, v85
	v_cvt_pk_bf16_f32 v35, v86, v87
	global_store_dwordx2 v[168:169], v[34:35], off offset:1536
	global_load_dwordx4 v[72:75], v[150:151], off nt
	global_load_dwordx4 v[76:79], v[150:151], off offset:1024 nt
	global_load_dwordx4 v[80:83], v[150:151], off offset:2048 nt
	global_load_dwordx4 v[84:87], v[150:151], off offset:3072 nt
	v_lshl_add_u64 v[150:151], v[150:151], 0, s[22:23]
	s_waitcnt vmcnt(16)
; __device__ __forceinline__ unsigned pk_bf16(float lo, float hi) { return pg8::cvt_pk_bf16(lo, hi); }
; __device__ __forceinline__ void norm0_phase(const Args& a, LAS unsigned char* lds, const int tid) {
;     ...
;             for (int k = 0; k < 8; ++k) {
;                 const int row = chunk * 8 + k;
;                 const float* xr = a.in[0] + (size_t)row * DM + 4 * lane;
;                 f32x4 v[4]; float ss = 0.f;
; #pragma unroll
;                 for (int j = 0; j < 4; ++j) { v[j] = __builtin_nontemporal_load((const f32x4*)(xr + 256 * j)); ss += (v[j][0] * v[j][0] + v[j][1] * v[j][1]) + (v[j][2] * v[j][2] + v[j][3] * v[j][3]); }
;                 ss = wave_sum(ss);
;                 if (lane == 0) *(f32x4*)(rowss + (size_t)row * 4) = (f32x4){ss, 0.f, 0.f, 0.f};
;                 bf16_t* hr = H + (size_t)row * DM + 4 * lane;
; #pragma unroll
;                 for (int j = 0; j < 4; ++j) {
;                     const f32x4 t = v[j] * sc1[j];
;                     u32x2 o; o.x = pk_bf16(t[0], t[1]); o.y = pk_bf16(t[2], t[3]);
;                     *(u32x2*)(hr + 256 * j) = o;
;                 }
	v_mul_f32_e32 v0, v89, v89
	v_mul_f32_e32 v2, v91, v91
	v_mul_f32_e32 v3, v93, v93
	v_mul_f32_e32 v43, v95, v95
	v_mul_f32_e32 v69, v97, v97
	v_mul_f32_e32 v128, v99, v99
	v_fmac_f32_e32 v0, v88, v88
	v_fmac_f32_e32 v2, v90, v90
	v_fmac_f32_e32 v3, v92, v92
	v_fmac_f32_e32 v43, v94, v94
	v_mul_f32_e32 v129, v101, v101
	v_mul_f32_e32 v148, v103, v103
	v_fmac_f32_e32 v69, v96, v96
	v_fmac_f32_e32 v128, v98, v98
	v_add_f32_e32 v0, v0, v2
	v_add_f32_e32 v2, v3, v43
	v_fmac_f32_e32 v129, v100, v100
	v_fmac_f32_e32 v148, v102, v102
	v_add_f32_e32 v3, v69, v128
	v_add_f32_e32 v0, v0, v2
	v_add_f32_e32 v0, v0, v3
	v_add_f32_e32 v2, v129, v148
	v_add_f32_e32 v121, v0, v2
	v_pk_mul_f32 v[88:89], v[54:55], v[88:89]
	v_pk_mul_f32 v[90:91], v[52:53], v[90:91]
	v_pk_mul_f32 v[92:93], v[58:59], v[92:93]
	v_pk_mul_f32 v[94:95], v[56:57], v[94:95]
	v_pk_mul_f32 v[96:97], v[62:63], v[96:97]
	v_pk_mul_f32 v[98:99], v[60:61], v[98:99]
	v_pk_mul_f32 v[100:101], v[66:67], v[100:101]
	v_pk_mul_f32 v[102:103], v[64:65], v[102:103]
	v_cvt_pk_bf16_f32 v176, v88, v89
	v_cvt_pk_bf16_f32 v177, v90, v91
	global_store_dwordx2 v[168:169], v[176:177], off offset:2048
	v_cvt_pk_bf16_f32 v178, v92, v93
	v_cvt_pk_bf16_f32 v179, v94, v95
	global_store_dwordx2 v[168:169], v[178:179], off offset:2560
	v_cvt_pk_bf16_f32 v180, v96, v97
	v_cvt_pk_bf16_f32 v181, v98, v99
	global_store_dwordx2 v[168:169], v[180:181], off offset:3072
	v_cvt_pk_bf16_f32 v182, v100, v101
	v_cvt_pk_bf16_f32 v183, v102, v103
	global_store_dwordx2 v[168:169], v[182:183], off offset:3584
	v_lshl_add_u64 v[168:169], v[168:169], 0, s[22:23]
	global_load_dwordx4 v[88:91], v[150:151], off nt
	global_load_dwordx4 v[92:95], v[150:151], off offset:1024 nt
	global_load_dwordx4 v[96:99], v[150:151], off offset:2048 nt
	global_load_dwordx4 v[100:103], v[150:151], off offset:3072 nt
	v_lshl_add_u64 v[150:151], v[150:151], 0, s[22:23]
	s_waitcnt vmcnt(20)
	v_mul_f32_e32 v0, v105, v105
	v_mul_f32_e32 v2, v107, v107
	v_mul_f32_e32 v3, v109, v109
	v_mul_f32_e32 v43, v111, v111
	v_mul_f32_e32 v69, v113, v113
	v_mul_f32_e32 v128, v115, v115
	v_fmac_f32_e32 v0, v104, v104
	v_fmac_f32_e32 v2, v106, v106
	v_fmac_f32_e32 v3, v108, v108
	v_fmac_f32_e32 v43, v110, v110
	v_mul_f32_e32 v129, v117, v117
	v_mul_f32_e32 v148, v119, v119
	v_fmac_f32_e32 v69, v112, v112
	v_fmac_f32_e32 v128, v114, v114
	v_add_f32_e32 v0, v0, v2
	v_add_f32_e32 v2, v3, v43
	v_fmac_f32_e32 v129, v116, v116
	v_fmac_f32_e32 v148, v118, v118
	v_add_f32_e32 v3, v69, v128
	v_add_f32_e32 v0, v0, v2
	v_add_f32_e32 v0, v0, v3
	v_add_f32_e32 v2, v129, v148
	v_add_f32_e32 v122, v0, v2
	v_pk_mul_f32 v[104:105], v[54:55], v[104:105]
	v_pk_mul_f32 v[106:107], v[52:53], v[106:107]
	v_pk_mul_f32 v[108:109], v[58:59], v[108:109]
	v_pk_mul_f32 v[110:111], v[56:57], v[110:111]
	v_pk_mul_f32 v[112:113], v[62:63], v[112:113]
	v_pk_mul_f32 v[114:115], v[60:61], v[114:115]
	v_pk_mul_f32 v[116:117], v[66:67], v[116:117]
	v_pk_mul_f32 v[118:119], v[64:65], v[118:119]
	v_cvt_pk_bf16_f32 v28, v104, v105
	v_cvt_pk_bf16_f32 v29, v106, v107
	global_store_dwordx2 v[168:169], v[28:29], off
	v_cvt_pk_bf16_f32 v30, v108, v109
	v_cvt_pk_bf16_f32 v31, v110, v111
	global_store_dwordx2 v[168:169], v[30:31], off offset:512
	v_cvt_pk_bf16_f32 v32, v112, v113
	v_cvt_pk_bf16_f32 v33, v114, v115
	global_store_dwordx2 v[168:169], v[32:33], off offset:1024
	v_cvt_pk_bf16_f32 v34, v116, v117
	v_cvt_pk_bf16_f32 v35, v118, v119
	global_store_dwordx2 v[168:169], v[34:35], off offset:1536
	global_load_dwordx4 v[104:107], v[150:151], off nt
	global_load_dwordx4 v[108:111], v[150:151], off offset:1024 nt
	global_load_dwordx4 v[112:115], v[150:151], off offset:2048 nt
	global_load_dwordx4 v[116:119], v[150:151], off offset:3072 nt
	v_lshl_add_u64 v[150:151], v[150:151], 0, s[22:23]
	s_waitcnt vmcnt(24)
	v_mul_f32_e32 v0, v133, v133
	v_mul_f32_e32 v2, v135, v135
	v_mul_f32_e32 v3, v137, v137
	v_mul_f32_e32 v43, v139, v139
	v_mul_f32_e32 v69, v141, v141
	v_mul_f32_e32 v128, v143, v143
	v_fmac_f32_e32 v0, v132, v132
	v_fmac_f32_e32 v2, v134, v134
	v_fmac_f32_e32 v3, v136, v136
	v_fmac_f32_e32 v43, v138, v138
	v_mul_f32_e32 v129, v145, v145
	v_mul_f32_e32 v148, v147, v147
	v_fmac_f32_e32 v69, v140, v140
	v_fmac_f32_e32 v128, v142, v142
	v_add_f32_e32 v0, v0, v2
	v_add_f32_e32 v2, v3, v43
	v_fmac_f32_e32 v129, v144, v144
	v_fmac_f32_e32 v148, v146, v146
	v_add_f32_e32 v3, v69, v128
	v_add_f32_e32 v0, v0, v2
	v_add_f32_e32 v0, v0, v3
	v_add_f32_e32 v2, v129, v148
	v_add_f32_e32 v123, v0, v2
	v_pk_mul_f32 v[132:133], v[54:55], v[132:133]
	v_pk_mul_f32 v[134:135], v[52:53], v[134:135]
	v_pk_mul_f32 v[136:137], v[58:59], v[136:137]
	v_pk_mul_f32 v[138:139], v[56:57], v[138:139]
	v_pk_mul_f32 v[140:141], v[62:63], v[140:141]
	v_pk_mul_f32 v[142:143], v[60:61], v[142:143]
	v_pk_mul_f32 v[144:145], v[66:67], v[144:145]
	v_pk_mul_f32 v[146:147], v[64:65], v[146:147]
	v_cvt_pk_bf16_f32 v176, v132, v133
	v_cvt_pk_bf16_f32 v177, v134, v135
	global_store_dwordx2 v[168:169], v[176:177], off offset:2048
	v_cvt_pk_bf16_f32 v178, v136, v137
	v_cvt_pk_bf16_f32 v179, v138, v139
	global_store_dwordx2 v[168:169], v[178:179], off offset:2560
	v_cvt_pk_bf16_f32 v180, v140, v141
	v_cvt_pk_bf16_f32 v181, v142, v143
	global_store_dwordx2 v[168:169], v[180:181], off offset:3072
	v_cvt_pk_bf16_f32 v182, v144, v145
	v_cvt_pk_bf16_f32 v183, v146, v147
	global_store_dwordx2 v[168:169], v[182:183], off offset:3584
	v_lshl_add_u64 v[168:169], v[168:169], 0, s[22:23]
	global_load_dwordx4 v[132:135], v[150:151], off nt
	global_load_dwordx4 v[136:139], v[150:151], off offset:1024 nt
	global_load_dwordx4 v[140:143], v[150:151], off offset:2048 nt
	global_load_dwordx4 v[144:147], v[150:151], off offset:3072 nt
	v_lshl_add_u64 v[150:151], v[150:151], 0, s[22:23]
	s_waitcnt vmcnt(24)
; __device__ __forceinline__ unsigned pk_bf16(float lo, float hi) { return pg8::cvt_pk_bf16(lo, hi); }
; __device__ __forceinline__ void norm0_phase(const Args& a, LAS unsigned char* lds, const int tid) {
;     ...
;             for (int k = 0; k < 8; ++k) {
;                 const int row = chunk * 8 + k;
;                 const float* xr = a.in[0] + (size_t)row * DM + 4 * lane;
;                 f32x4 v[4]; float ss = 0.f;
; #pragma unroll
;                 for (int j = 0; j < 4; ++j) { v[j] = __builtin_nontemporal_load((const f32x4*)(xr + 256 * j)); ss += (v[j][0] * v[j][0] + v[j][1] * v[j][1]) + (v[j][2] * v[j][2] + v[j][3] * v[j][3]); }
;                 ss = wave_sum(ss);
;                 if (lane == 0) *(f32x4*)(rowss + (size_t)row * 4) = (f32x4){ss, 0.f, 0.f, 0.f};
;                 bf16_t* hr = H + (size_t)row * DM + 4 * lane;
; #pragma unroll
;                 for (int j = 0; j < 4; ++j) {
;                     const f32x4 t = v[j] * sc1[j];
;                     u32x2 o; o.x = pk_bf16(t[0], t[1]); o.y = pk_bf16(t[2], t[3]);
;                     *(u32x2*)(hr + 256 * j) = o;
;                 }
	v_mul_f32_e32 v0, v73, v73
	v_mul_f32_e32 v2, v75, v75
	v_mul_f32_e32 v3, v77, v77
	v_mul_f32_e32 v43, v79, v79
	v_mul_f32_e32 v69, v81, v81
	v_mul_f32_e32 v128, v83, v83
	v_fmac_f32_e32 v0, v72, v72
	v_fmac_f32_e32 v2, v74, v74
	v_fmac_f32_e32 v3, v76, v76
	v_fmac_f32_e32 v43, v78, v78
	v_mul_f32_e32 v129, v85, v85
	v_mul_f32_e32 v148, v87, v87
	v_fmac_f32_e32 v69, v80, v80
	v_fmac_f32_e32 v128, v82, v82
	v_add_f32_e32 v0, v0, v2
	v_add_f32_e32 v2, v3, v43
	v_fmac_f32_e32 v129, v84, v84
	v_fmac_f32_e32 v148, v86, v86
	v_add_f32_e32 v3, v69, v128
	v_add_f32_e32 v0, v0, v2
	v_add_f32_e32 v0, v0, v3
	v_add_f32_e32 v2, v129, v148
	v_add_f32_e32 v124, v0, v2
	v_pk_mul_f32 v[72:73], v[54:55], v[72:73]
	v_pk_mul_f32 v[74:75], v[52:53], v[74:75]
	v_pk_mul_f32 v[76:77], v[58:59], v[76:77]
	v_pk_mul_f32 v[78:79], v[56:57], v[78:79]
	v_pk_mul_f32 v[80:81], v[62:63], v[80:81]
	v_pk_mul_f32 v[82:83], v[60:61], v[82:83]
	v_pk_mul_f32 v[84:85], v[66:67], v[84:85]
	v_pk_mul_f32 v[86:87], v[64:65], v[86:87]
	v_cvt_pk_bf16_f32 v28, v72, v73
	v_cvt_pk_bf16_f32 v29, v74, v75
	global_store_dwordx2 v[168:169], v[28:29], off
	v_cvt_pk_bf16_f32 v30, v76, v77
	v_cvt_pk_bf16_f32 v31, v78, v79
	global_store_dwordx2 v[168:169], v[30:31], off offset:512
	v_cvt_pk_bf16_f32 v32, v80, v81
	v_cvt_pk_bf16_f32 v33, v82, v83
	global_store_dwordx2 v[168:169], v[32:33], off offset:1024
	v_cvt_pk_bf16_f32 v34, v84, v85
	v_cvt_pk_bf16_f32 v35, v86, v87
	global_store_dwordx2 v[168:169], v[34:35], off offset:1536
	s_waitcnt vmcnt(20)
	v_mul_f32_e32 v0, v89, v89
	v_mul_f32_e32 v2, v91, v91
	v_mul_f32_e32 v3, v93, v93
	v_mul_f32_e32 v43, v95, v95
	v_mul_f32_e32 v69, v97, v97
	v_mul_f32_e32 v128, v99, v99
	v_fmac_f32_e32 v0, v88, v88
	v_fmac_f32_e32 v2, v90, v90
	v_fmac_f32_e32 v3, v92, v92
	v_fmac_f32_e32 v43, v94, v94
	v_mul_f32_e32 v129, v101, v101
	v_mul_f32_e32 v148, v103, v103
	v_fmac_f32_e32 v69, v96, v96
	v_fmac_f32_e32 v128, v98, v98
	v_add_f32_e32 v0, v0, v2
	v_add_f32_e32 v2, v3, v43
	v_fmac_f32_e32 v129, v100, v100
	v_fmac_f32_e32 v148, v102, v102
	v_add_f32_e32 v3, v69, v128
	v_add_f32_e32 v0, v0, v2
	v_add_f32_e32 v0, v0, v3
	v_add_f32_e32 v2, v129, v148
	v_add_f32_e32 v125, v0, v2
	v_pk_mul_f32 v[88:89], v[54:55], v[88:89]
	v_pk_mul_f32 v[90:91], v[52:53], v[90:91]
	v_pk_mul_f32 v[92:93], v[58:59], v[92:93]
	v_pk_mul_f32 v[94:95], v[56:57], v[94:95]
	v_pk_mul_f32 v[96:97], v[62:63], v[96:97]
	v_pk_mul_f32 v[98:99], v[60:61], v[98:99]
	v_pk_mul_f32 v[100:101], v[66:67], v[100:101]
	v_pk_mul_f32 v[102:103], v[64:65], v[102:103]
	v_cvt_pk_bf16_f32 v176, v88, v89
	v_cvt_pk_bf16_f32 v177, v90, v91
	global_store_dwordx2 v[168:169], v[176:177], off offset:2048
	v_cvt_pk_bf16_f32 v178, v92, v93
	v_cvt_pk_bf16_f32 v179, v94, v95
	global_store_dwordx2 v[168:169], v[178:179], off offset:2560
	v_cvt_pk_bf16_f32 v180, v96, v97
	v_cvt_pk_bf16_f32 v181, v98, v99
	global_store_dwordx2 v[168:169], v[180:181], off offset:3072
	v_cvt_pk_bf16_f32 v182, v100, v101
	v_cvt_pk_bf16_f32 v183, v102, v103
	global_store_dwordx2 v[168:169], v[182:183], off offset:3584
	v_lshl_add_u64 v[168:169], v[168:169], 0, s[22:23]
	s_waitcnt vmcnt(16)
	v_mul_f32_e32 v0, v105, v105
	v_mul_f32_e32 v2, v107, v107
	v_mul_f32_e32 v3, v109, v109
	v_mul_f32_e32 v43, v111, v111
	v_mul_f32_e32 v69, v113, v113
	v_mul_f32_e32 v128, v115, v115
	v_fmac_f32_e32 v0, v104, v104
	v_fmac_f32_e32 v2, v106, v106
	v_fmac_f32_e32 v3, v108, v108
	v_fmac_f32_e32 v43, v110, v110
	v_mul_f32_e32 v129, v117, v117
	v_mul_f32_e32 v148, v119, v119
	v_fmac_f32_e32 v69, v112, v112
	v_fmac_f32_e32 v128, v114, v114
	v_add_f32_e32 v0, v0, v2
	v_add_f32_e32 v2, v3, v43
	v_fmac_f32_e32 v129, v116, v116
	v_fmac_f32_e32 v148, v118, v118
	v_add_f32_e32 v3, v69, v128
	v_add_f32_e32 v0, v0, v2
	v_add_f32_e32 v0, v0, v3
	v_add_f32_e32 v2, v129, v148
	v_add_f32_e32 v126, v0, v2
	v_pk_mul_f32 v[104:105], v[54:55], v[104:105]
	v_pk_mul_f32 v[106:107], v[52:53], v[106:107]
	v_pk_mul_f32 v[108:109], v[58:59], v[108:109]
	v_pk_mul_f32 v[110:111], v[56:57], v[110:111]
	v_pk_mul_f32 v[112:113], v[62:63], v[112:113]
	v_pk_mul_f32 v[114:115], v[60:61], v[114:115]
	v_pk_mul_f32 v[116:117], v[66:67], v[116:117]
	v_pk_mul_f32 v[118:119], v[64:65], v[118:119]
	v_cvt_pk_bf16_f32 v28, v104, v105
	v_cvt_pk_bf16_f32 v29, v106, v107
	global_store_dwordx2 v[168:169], v[28:29], off
	v_cvt_pk_bf16_f32 v30, v108, v109
	v_cvt_pk_bf16_f32 v31, v110, v111
	global_store_dwordx2 v[168:169], v[30:31], off offset:512
	v_cvt_pk_bf16_f32 v32, v112, v113
	v_cvt_pk_bf16_f32 v33, v114, v115
	global_store_dwordx2 v[168:169], v[32:33], off offset:1024
	v_cvt_pk_bf16_f32 v34, v116, v117
	v_cvt_pk_bf16_f32 v35, v118, v119
	global_store_dwordx2 v[168:169], v[34:35], off offset:1536
	s_waitcnt vmcnt(12)
; __device__ __forceinline__ float wave_sum(float v) {
; #pragma unroll
;     for (int o = 1; o < 64; o <<= 1) v += __shfl_xor(v, o);
;     return v;
; __device__ __forceinline__ void norm0_phase(const Args& a, LAS unsigned char* lds, const int tid) {
;     ...
;                 ss = wave_sum(ss);
;                 if (lane == 0) *(f32x4*)(rowss + (size_t)row * 4) = (f32x4){ss, 0.f, 0.f, 0.f};
	v_mul_f32_e32 v0, v133, v133
	v_mul_f32_e32 v2, v135, v135
	v_mul_f32_e32 v3, v137, v137
	v_mul_f32_e32 v43, v139, v139
	v_mul_f32_e32 v69, v141, v141
	v_mul_f32_e32 v128, v143, v143
	v_fmac_f32_e32 v0, v132, v132
	v_fmac_f32_e32 v2, v134, v134
	v_fmac_f32_e32 v3, v136, v136
	v_fmac_f32_e32 v43, v138, v138
	v_mul_f32_e32 v129, v145, v145
	v_mul_f32_e32 v148, v147, v147
	v_fmac_f32_e32 v69, v140, v140
	v_fmac_f32_e32 v128, v142, v142
	v_add_f32_e32 v0, v0, v2
	v_add_f32_e32 v2, v3, v43
	v_fmac_f32_e32 v129, v144, v144
	v_fmac_f32_e32 v148, v146, v146
	v_add_f32_e32 v3, v69, v128
	v_add_f32_e32 v0, v0, v2
	v_add_f32_e32 v0, v0, v3
	v_add_f32_e32 v2, v129, v148
	v_add_f32_e32 v127, v0, v2
	v_pk_mul_f32 v[132:133], v[54:55], v[132:133]
	v_pk_mul_f32 v[134:135], v[52:53], v[134:135]
	v_pk_mul_f32 v[136:137], v[58:59], v[136:137]
	v_pk_mul_f32 v[138:139], v[56:57], v[138:139]
	v_pk_mul_f32 v[140:141], v[62:63], v[140:141]
	v_pk_mul_f32 v[142:143], v[60:61], v[142:143]
	v_pk_mul_f32 v[144:145], v[66:67], v[144:145]
	v_pk_mul_f32 v[146:147], v[64:65], v[146:147]
	v_cvt_pk_bf16_f32 v176, v132, v133
	v_cvt_pk_bf16_f32 v177, v134, v135
	global_store_dwordx2 v[168:169], v[176:177], off offset:2048
	v_cvt_pk_bf16_f32 v178, v136, v137
	v_cvt_pk_bf16_f32 v179, v138, v139
	global_store_dwordx2 v[168:169], v[178:179], off offset:2560
	v_cvt_pk_bf16_f32 v180, v140, v141
	v_cvt_pk_bf16_f32 v181, v142, v143
	global_store_dwordx2 v[168:169], v[180:181], off offset:3072
	v_cvt_pk_bf16_f32 v182, v144, v145
	v_cvt_pk_bf16_f32 v183, v146, v147
	global_store_dwordx2 v[168:169], v[182:183], off offset:3584
	v_lshl_add_u64 v[168:169], v[168:169], 0, s[22:23]
	ds_bpermute_b32 v20, v219, v120
	ds_bpermute_b32 v21, v219, v121
	ds_bpermute_b32 v22, v219, v122
	ds_bpermute_b32 v23, v219, v123
	ds_bpermute_b32 v24, v219, v124
	ds_bpermute_b32 v25, v219, v125
	ds_bpermute_b32 v26, v219, v126
	ds_bpermute_b32 v27, v219, v127
	s_waitcnt lgkmcnt(7)
	v_add_f32_e32 v120, v120, v20
	s_waitcnt lgkmcnt(6)
	v_add_f32_e32 v121, v121, v21
	s_waitcnt lgkmcnt(5)
	v_add_f32_e32 v122, v122, v22
	s_waitcnt lgkmcnt(4)
	v_add_f32_e32 v123, v123, v23
	s_waitcnt lgkmcnt(3)
	v_add_f32_e32 v124, v124, v24
	s_waitcnt lgkmcnt(2)
	v_add_f32_e32 v125, v125, v25
	s_waitcnt lgkmcnt(1)
	v_add_f32_e32 v126, v126, v26
	s_waitcnt lgkmcnt(0)
	v_add_f32_e32 v127, v127, v27
	ds_bpermute_b32 v20, v220, v120
	ds_bpermute_b32 v21, v220, v121
	ds_bpermute_b32 v22, v220, v122
	ds_bpermute_b32 v23, v220, v123
	ds_bpermute_b32 v24, v220, v124
	ds_bpermute_b32 v25, v220, v125
	ds_bpermute_b32 v26, v220, v126
	ds_bpermute_b32 v27, v220, v127
	s_waitcnt lgkmcnt(7)
	v_add_f32_e32 v120, v120, v20
	s_waitcnt lgkmcnt(6)
	v_add_f32_e32 v121, v121, v21
	s_waitcnt lgkmcnt(5)
	v_add_f32_e32 v122, v122, v22
	s_waitcnt lgkmcnt(4)
	v_add_f32_e32 v123, v123, v23
	s_waitcnt lgkmcnt(3)
	v_add_f32_e32 v124, v124, v24
	s_waitcnt lgkmcnt(2)
	v_add_f32_e32 v125, v125, v25
	s_waitcnt lgkmcnt(1)
	v_add_f32_e32 v126, v126, v26
	s_waitcnt lgkmcnt(0)
	v_add_f32_e32 v127, v127, v27
	ds_bpermute_b32 v20, v221, v120
	ds_bpermute_b32 v21, v221, v121
	ds_bpermute_b32 v22, v221, v122
	ds_bpermute_b32 v23, v221, v123
	ds_bpermute_b32 v24, v221, v124
	ds_bpermute_b32 v25, v221, v125
	ds_bpermute_b32 v26, v221, v126
	ds_bpermute_b32 v27, v221, v127
	s_waitcnt lgkmcnt(7)
	v_add_f32_e32 v120, v120, v20
	s_waitcnt lgkmcnt(6)
	v_add_f32_e32 v121, v121, v21
	s_waitcnt lgkmcnt(5)
	v_add_f32_e32 v122, v122, v22
	s_waitcnt lgkmcnt(4)
	v_add_f32_e32 v123, v123, v23
	s_waitcnt lgkmcnt(3)
	v_add_f32_e32 v124, v124, v24
	s_waitcnt lgkmcnt(2)
	v_add_f32_e32 v125, v125, v25
	s_waitcnt lgkmcnt(1)
	v_add_f32_e32 v126, v126, v26
	s_waitcnt lgkmcnt(0)
	v_add_f32_e32 v127, v127, v27
	ds_bpermute_b32 v20, v222, v120
	ds_bpermute_b32 v21, v222, v121
	ds_bpermute_b32 v22, v222, v122
	ds_bpermute_b32 v23, v222, v123
	ds_bpermute_b32 v24, v222, v124
	ds_bpermute_b32 v25, v222, v125
	ds_bpermute_b32 v26, v222, v126
	ds_bpermute_b32 v27, v222, v127
	s_waitcnt lgkmcnt(7)
	v_add_f32_e32 v120, v120, v20
	s_waitcnt lgkmcnt(6)
	v_add_f32_e32 v121, v121, v21
	s_waitcnt lgkmcnt(5)
	v_add_f32_e32 v122, v122, v22
	s_waitcnt lgkmcnt(4)
	v_add_f32_e32 v123, v123, v23
	s_waitcnt lgkmcnt(3)
	v_add_f32_e32 v124, v124, v24
	s_waitcnt lgkmcnt(2)
	v_add_f32_e32 v125, v125, v25
	s_waitcnt lgkmcnt(1)
	v_add_f32_e32 v126, v126, v26
	s_waitcnt lgkmcnt(0)
	v_add_f32_e32 v127, v127, v27
	ds_bpermute_b32 v20, v223, v120
	ds_bpermute_b32 v21, v223, v121
	ds_bpermute_b32 v22, v223, v122
	ds_bpermute_b32 v23, v223, v123
	ds_bpermute_b32 v24, v223, v124
	ds_bpermute_b32 v25, v223, v125
	ds_bpermute_b32 v26, v223, v126
	ds_bpermute_b32 v27, v223, v127
	s_waitcnt lgkmcnt(7)
	v_add_f32_e32 v120, v120, v20
	s_waitcnt lgkmcnt(6)
	v_add_f32_e32 v121, v121, v21
	s_waitcnt lgkmcnt(5)
	v_add_f32_e32 v122, v122, v22
	s_waitcnt lgkmcnt(4)
	v_add_f32_e32 v123, v123, v23
	s_waitcnt lgkmcnt(3)
	v_add_f32_e32 v124, v124, v24
	s_waitcnt lgkmcnt(2)
	v_add_f32_e32 v125, v125, v25
	s_waitcnt lgkmcnt(1)
	v_add_f32_e32 v126, v126, v26
	s_waitcnt lgkmcnt(0)
	v_add_f32_e32 v127, v127, v27
	ds_bpermute_b32 v20, v224, v120
	ds_bpermute_b32 v21, v224, v121
	ds_bpermute_b32 v22, v224, v122
	ds_bpermute_b32 v23, v224, v123
	ds_bpermute_b32 v24, v224, v124
	ds_bpermute_b32 v25, v224, v125
	ds_bpermute_b32 v26, v224, v126
	ds_bpermute_b32 v27, v224, v127
	s_waitcnt lgkmcnt(7)
	v_add_f32_e32 v120, v120, v20
	s_waitcnt lgkmcnt(6)
	v_add_f32_e32 v121, v121, v21
	s_waitcnt lgkmcnt(5)
	v_add_f32_e32 v122, v122, v22
	s_waitcnt lgkmcnt(4)
	v_add_f32_e32 v123, v123, v23
	s_waitcnt lgkmcnt(3)
	v_add_f32_e32 v124, v124, v24
	s_waitcnt lgkmcnt(2)
	v_add_f32_e32 v125, v125, v25
	s_waitcnt lgkmcnt(1)
	v_add_f32_e32 v126, v126, v26
	s_waitcnt lgkmcnt(0)
	v_add_f32_e32 v127, v127, v27
	v_mov_b32_e32 v28, v120
	v_cmp_eq_u32_e32 vcc, 1, v70
	s_nop 1
	v_cndmask_b32_e32 v28, v28, v121, vcc
	v_cmp_eq_u32_e32 vcc, 2, v70
	s_nop 1
	v_cndmask_b32_e32 v28, v28, v122, vcc
	v_cmp_eq_u32_e32 vcc, 3, v70
	s_nop 1
	v_cndmask_b32_e32 v28, v28, v123, vcc
	v_cmp_eq_u32_e32 vcc, 4, v70
	s_nop 1
	v_cndmask_b32_e32 v28, v28, v124, vcc
	v_cmp_eq_u32_e32 vcc, 5, v70
	s_nop 1
	v_cndmask_b32_e32 v28, v28, v125, vcc
	v_cmp_eq_u32_e32 vcc, 6, v70
	s_nop 1
	v_cndmask_b32_e32 v28, v28, v126, vcc
	v_cmp_eq_u32_e32 vcc, 7, v70
	s_nop 1
	v_cndmask_b32_e32 v28, v28, v127, vcc
	v_mov_b32_e32 v29, v1
	v_mov_b32_e32 v30, v1
	v_mov_b32_e32 v31, v1
	v_lshlrev_b32_e32 v2, 4, v70
	v_mov_b32_e32 v3, v1
	v_lshl_add_u64 v[170:171], s[46:47], 0, v[46:47]
	v_lshl_add_u64 v[170:171], v[170:171], 0, v[2:3]
	v_cmp_gt_u32_e32 vcc, 8, v70
	s_nop 1
	s_and_saveexec_b64 s[10:11], vcc
	global_store_dwordx4 v[170:171], v[28:31], off
	s_mov_b64 exec, s[10:11]
	s_branch .LBB0_28

; __device__ __forceinline__ void shw_tables(const Args& a, int t_lo, int t_hi, int gw, int ngw, int lane) {
;     ...
;         for (int t = t_lo; t < t_hi; ++t) {
;             const int l = t >> 1, type = t & 1, nrows = type ? 2 * FF : UW;
;             const float* sh = mod + (size_t)l * 8 * MODW + (type ? 3072 : 0) + 16 * lane;
;             const bf16_t* wbase = type ? (const bf16_t*)(ws + WS_WGU) + (size_t)l * 2 * FF * 1024 : (const bf16_t*)(ws + WS_WIN) + (size_t)l * UW * 1024;
;             float* outp = type ? (float*)(ws + WS_SHW2) + (size_t)l * 8 * 2 * FF : (float*)(ws + WS_SHW1) + (size_t)l * 8 * UW;
;             f32x4 sv[8][4];
; #pragma unroll
;             for (int b = 0; b < 8; ++b)
; #pragma unroll
;                 for (int q = 0; q < 4; ++q) sv[b][q] = *(const f32x4*)(sh + (size_t)b * MODW + 4 * q);
;             for (int r = gw; r < nrows; r += ngw) {
;                 const bf16_t* wrow = wbase + (size_t)r * 1024 + 16 * lane;
;                 const u32x4 w0 = *(const u32x4*)(wrow), w1 = *(const u32x4*)(wrow + 8);
.LBB0_40:
	s_and_b64 s[30:31], s[10:11], exec
	s_cselect_b32 s27, s77, 0x1600
	v_cmp_gt_i32_e32 vcc, s27, v130
	s_and_saveexec_b64 s[38:39], vcc
	s_cbranch_execz .LBB0_39
	s_and_b64 s[30:31], s[10:11], exec
	s_cselect_b32 s30, 0, 0x3000
	s_mov_b32 s31, s21
	v_lshl_add_u64 v[126:127], v[132:133], 0, s[30:31]
	v_add_co_u32_e32 v10, vcc, 0x2a000, v126
	s_mov_b64 s[30:31], 0x2a000
	s_nop 0
	v_addc_co_u32_e32 v11, vcc, 0, v127, vcc
	v_add_co_u32_e32 v26, vcc, s55, v126
	v_lshl_add_u64 v[14:15], v[126:127], 0, s[30:31]
	s_nop 0
	v_addc_co_u32_e32 v27, vcc, 0, v127, vcc
	v_add_co_u32_e32 v42, vcc, s51, v126
	s_mov_b64 s[30:31], 0x24000
	s_nop 0
	v_addc_co_u32_e32 v43, vcc, 0, v127, vcc
	v_add_co_u32_e32 v58, vcc, s82, v126
	v_lshl_add_u64 v[30:31], v[126:127], 0, s[30:31]
	s_nop 0
	v_addc_co_u32_e32 v59, vcc, 0, v127, vcc
	s_mov_b64 s[30:31], 0x1e000
	v_add_co_u32_e32 v74, vcc, s33, v126
	v_lshl_add_u64 v[46:47], v[126:127], 0, s[30:31]
	s_mov_b64 s[30:31], 0x18000
	v_addc_co_u32_e32 v75, vcc, 0, v127, vcc
	v_lshl_add_u64 v[62:63], v[126:127], 0, s[30:31]
	s_mov_b64 s[30:31], 0x12000
	v_add_co_u32_e32 v90, vcc, s54, v126
	v_lshl_add_u64 v[78:79], v[126:127], 0, s[30:31]
	s_mov_b64 s[30:31], 0xc000
	v_addc_co_u32_e32 v91, vcc, 0, v127, vcc
	v_lshl_add_u64 v[94:95], v[126:127], 0, s[30:31]
	v_add_co_u32_e32 v106, vcc, s96, v126
	s_mov_b64 s[30:31], 0x6000
	s_nop 0
	v_addc_co_u32_e32 v107, vcc, 0, v127, vcc
	v_lshl_add_u64 v[110:111], v[126:127], 0, s[30:31]
	global_load_dwordx4 v[2:5], v[14:15], off offset:16
	global_load_dwordx4 v[6:9], v[14:15], off offset:32
	s_nop 0
	global_load_dwordx4 v[10:13], v[10:11], off
	s_nop 0
	global_load_dwordx4 v[14:17], v[14:15], off offset:48
	s_nop 0
	global_load_dwordx4 v[18:21], v[30:31], off offset:16
	global_load_dwordx4 v[22:25], v[30:31], off offset:32
	s_nop 0
	global_load_dwordx4 v[26:29], v[26:27], off
	s_nop 0
	global_load_dwordx4 v[30:33], v[30:31], off offset:48
	s_nop 0
	global_load_dwordx4 v[34:37], v[46:47], off offset:16
	global_load_dwordx4 v[38:41], v[46:47], off offset:32
	s_nop 0
	global_load_dwordx4 v[42:45], v[42:43], off
	s_nop 0
	global_load_dwordx4 v[46:49], v[46:47], off offset:48
	s_nop 0
	global_load_dwordx4 v[50:53], v[62:63], off offset:16
	global_load_dwordx4 v[54:57], v[62:63], off offset:32
	s_nop 0
	global_load_dwordx4 v[58:61], v[58:59], off
	s_nop 0
	global_load_dwordx4 v[62:65], v[62:63], off offset:48
	s_nop 0
	global_load_dwordx4 v[66:69], v[78:79], off offset:16
	global_load_dwordx4 v[70:73], v[78:79], off offset:32
	s_nop 0
	global_load_dwordx4 v[74:77], v[74:75], off
	s_nop 0
	global_load_dwordx4 v[78:81], v[78:79], off offset:48
	s_nop 0
	global_load_dwordx4 v[82:85], v[94:95], off offset:16
	global_load_dwordx4 v[86:89], v[94:95], off offset:32
	s_nop 0
	global_load_dwordx4 v[90:93], v[90:91], off
	s_nop 0
	global_load_dwordx4 v[94:97], v[94:95], off offset:48
	s_nop 0
	global_load_dwordx4 v[98:101], v[110:111], off offset:16
	global_load_dwordx4 v[102:105], v[110:111], off offset:32
	s_nop 0
	global_load_dwordx4 v[106:109], v[106:107], off
	s_nop 0
	global_load_dwordx4 v[110:113], v[110:111], off offset:48
	s_nop 0
	global_load_dwordx4 v[114:117], v[126:127], off
	global_load_dwordx4 v[118:121], v[126:127], off offset:16
	global_load_dwordx4 v[122:125], v[126:127], off offset:32
	s_nop 0
	global_load_dwordx4 v[126:129], v[126:127], off offset:48
	s_mov_b32 s30, 0xd800000
	s_mov_b32 s20, 0x400000
	s_cselect_b32 s30, s30, 0xd900000
	v_mul_u32_u24_e32 v0, s27, v142
	s_cselect_b32 s20, s20, 0x1400000
	v_lshl_or_b32 v0, v0, 2, s30
	s_mov_b64 s[40:41], 0
	v_mov_b32_e32 v131, v130
	v_lshl_add_u64 v[138:139], v[134:135], 0, v[0:1]
	v_lshl_add_u64 v[140:141], v[136:137], 0, s[20:21]
	global_load_dwordx4 v[168:171], v[140:141], off
	global_load_dwordx4 v[172:175], v[140:141], off offset:-16
	s_waitcnt vmcnt(0)
	s_branch .LBB0_43

; __device__ __forceinline__ void shw_tables(const Args& a, int t_lo, int t_hi, int gw, int ngw, int lane) {
;     ...
;             for (int r = gw; r < nrows; r += ngw) {
;                 const bf16_t* wrow = wbase + (size_t)r * 1024 + 16 * lane;
;                 const u32x4 w0 = *(const u32x4*)(wrow), w1 = *(const u32x4*)(wrow + 8);
;                 float wf[16];
; #pragma unroll
;                 for (int i = 0; i < 4; ++i) { wf[2 * i] = __uint_as_float(w0[i] << 16); wf[2 * i + 1] = __uint_as_float(w0[i] & 0xffff0000u); wf[8 + 2 * i] = __uint_as_float(w1[i] << 16); wf[8 + 2 * i + 1] = __uint_as_float(w1[i] & 0xffff0000u); }
;                 float d8[8];
; #pragma unroll
;                 for (int b = 0; b < 8; ++b) { float d = 0.f;
; #pragma unroll
;                     for (int q = 0; q < 4; ++q) d += (sv[b][q][0] * wf[4 * q] + sv[b][q][1] * wf[4 * q + 1]) + (sv[b][q][2] * wf[4 * q + 2] + sv[b][q][3] * wf[4 * q + 3]);
;                     d8[b] = d; }
.LBB0_43:
	s_waitcnt vmcnt(1)
	v_lshlrev_b32_e32 v0, 16, v168
	v_and_b32_e32 v154, 0xffff0000, v172
	v_and_b32_e32 v146, 0xffff0000, v168
	v_and_b32_e32 v156, 0xffff0000, v173
	v_lshlrev_b32_e32 v150, 16, v172
	v_lshlrev_b32_e32 v152, 16, v173
	s_waitcnt lgkmcnt(0)
	v_lshlrev_b32_e32 v143, 16, v170
	v_and_b32_e32 v147, 0xffff0000, v170
	v_lshlrev_b32_e32 v145, 16, v171
	v_and_b32_e32 v149, 0xffff0000, v171
	v_mul_f32_e32 v158, v115, v154
	v_mul_f32_e32 v159, v117, v156
	v_lshlrev_b32_e32 v144, 16, v169
	v_and_b32_e32 v148, 0xffff0000, v169
	v_and_b32_e32 v155, 0xffff0000, v174
	v_and_b32_e32 v157, 0xffff0000, v175
	v_fmac_f32_e32 v158, v114, v150
	v_fmac_f32_e32 v159, v116, v152
	v_lshlrev_b32_e32 v151, 16, v174
	v_lshlrev_b32_e32 v153, 16, v175
	v_lshl_add_u64 v[176:177], v[140:141], 0, s[14:15]
	global_load_dwordx4 v[168:171], v[176:177], off
	global_load_dwordx4 v[172:175], v[176:177], off offset:-16
	v_add_f32_e32 v158, v158, v159
	v_mul_f32_e32 v159, v119, v155
	v_mul_f32_e32 v160, v121, v157
	v_fmac_f32_e32 v159, v118, v151
	v_fmac_f32_e32 v160, v120, v153
	v_add_f32_e32 v158, 0, v158
	v_add_f32_e32 v159, v159, v160
	v_add_f32_e32 v158, v159, v158
	v_mul_f32_e32 v159, v123, v146
	v_mul_f32_e32 v160, v125, v148
	v_fmac_f32_e32 v159, v122, v0
	v_fmac_f32_e32 v160, v124, v144
	v_add_f32_e32 v159, v159, v160
	v_add_f32_e32 v158, v159, v158
	v_mul_f32_e32 v159, v127, v147
	v_mul_f32_e32 v160, v129, v149
	v_fmac_f32_e32 v159, v126, v143
	v_fmac_f32_e32 v160, v128, v145
	v_add_f32_e32 v159, v159, v160
	v_add_f32_e32 v158, v159, v158
	v_mul_f32_e32 v159, v107, v154
	v_mul_f32_e32 v160, v109, v156
	v_fmac_f32_e32 v159, v106, v150
	v_fmac_f32_e32 v160, v108, v152
	v_add_f32_e32 v159, v159, v160
	v_mul_f32_e32 v160, v99, v155
	v_mul_f32_e32 v161, v101, v157
	v_fmac_f32_e32 v160, v98, v151
	v_fmac_f32_e32 v161, v100, v153
	v_add_f32_e32 v159, 0, v159
	v_add_f32_e32 v160, v160, v161
	v_add_f32_e32 v159, v160, v159
	v_mul_f32_e32 v160, v103, v146
	v_mul_f32_e32 v161, v105, v148
	v_fmac_f32_e32 v160, v102, v0
	v_fmac_f32_e32 v161, v104, v144
	v_add_f32_e32 v160, v160, v161
	v_add_f32_e32 v159, v160, v159
	v_mul_f32_e32 v160, v111, v147
	v_mul_f32_e32 v161, v113, v149
	v_fmac_f32_e32 v160, v110, v143
	v_fmac_f32_e32 v161, v112, v145
	v_add_f32_e32 v160, v160, v161
	v_add_f32_e32 v159, v160, v159
	v_mul_f32_e32 v160, v91, v154
	v_mul_f32_e32 v161, v93, v156
	v_fmac_f32_e32 v160, v90, v150
	v_fmac_f32_e32 v161, v92, v152
	v_add_f32_e32 v160, v160, v161
	v_mul_f32_e32 v161, v83, v155
	v_mul_f32_e32 v162, v85, v157
	v_fmac_f32_e32 v161, v82, v151
	v_fmac_f32_e32 v162, v84, v153
	v_add_f32_e32 v160, 0, v160
	v_add_f32_e32 v161, v161, v162
	v_add_f32_e32 v160, v161, v160
	v_mul_f32_e32 v161, v87, v146
	v_mul_f32_e32 v162, v89, v148
	v_fmac_f32_e32 v161, v86, v0
	v_fmac_f32_e32 v162, v88, v144
	v_add_f32_e32 v161, v161, v162
	v_add_f32_e32 v160, v161, v160
	v_mul_f32_e32 v161, v95, v147
	v_mul_f32_e32 v162, v97, v149
	v_fmac_f32_e32 v161, v94, v143
	v_fmac_f32_e32 v162, v96, v145
	v_add_f32_e32 v161, v161, v162
	v_add_f32_e32 v160, v161, v160
	v_mul_f32_e32 v161, v75, v154
	v_mul_f32_e32 v162, v77, v156
	v_fmac_f32_e32 v161, v74, v150
	v_fmac_f32_e32 v162, v76, v152
	v_add_f32_e32 v161, v161, v162
	v_mul_f32_e32 v162, v67, v155
	v_mul_f32_e32 v163, v69, v157
	v_fmac_f32_e32 v162, v66, v151
	v_fmac_f32_e32 v163, v68, v153
	v_add_f32_e32 v161, 0, v161
	v_add_f32_e32 v162, v162, v163
	v_add_f32_e32 v161, v162, v161
	v_mul_f32_e32 v162, v71, v146
	v_mul_f32_e32 v163, v73, v148
	v_fmac_f32_e32 v162, v70, v0
	v_fmac_f32_e32 v163, v72, v144
	v_add_f32_e32 v162, v162, v163
	v_add_f32_e32 v161, v162, v161
	v_mul_f32_e32 v162, v79, v147
	v_mul_f32_e32 v163, v81, v149
	v_fmac_f32_e32 v162, v78, v143
	v_fmac_f32_e32 v163, v80, v145
	v_add_f32_e32 v162, v162, v163
	v_add_f32_e32 v161, v162, v161
	v_mul_f32_e32 v162, v59, v154
	v_mul_f32_e32 v163, v61, v156
	v_fmac_f32_e32 v162, v58, v150
	v_fmac_f32_e32 v163, v60, v152
	v_add_f32_e32 v162, v162, v163
	v_mul_f32_e32 v163, v51, v155
	v_mul_f32_e32 v164, v53, v157
	v_fmac_f32_e32 v163, v50, v151
	v_fmac_f32_e32 v164, v52, v153
	v_add_f32_e32 v162, 0, v162
	v_add_f32_e32 v163, v163, v164
	v_add_f32_e32 v162, v163, v162
	v_mul_f32_e32 v163, v55, v146
	v_mul_f32_e32 v164, v57, v148
	v_fmac_f32_e32 v163, v54, v0
	v_fmac_f32_e32 v164, v56, v144
	v_add_f32_e32 v163, v163, v164
	v_add_f32_e32 v162, v163, v162
	v_mul_f32_e32 v163, v63, v147
	v_mul_f32_e32 v164, v65, v149
	v_fmac_f32_e32 v163, v62, v143
	v_fmac_f32_e32 v164, v64, v145
	v_add_f32_e32 v163, v163, v164
	v_add_f32_e32 v162, v163, v162
	v_mul_f32_e32 v163, v43, v154
	v_mul_f32_e32 v164, v45, v156
	v_fmac_f32_e32 v163, v42, v150
	v_fmac_f32_e32 v164, v44, v152
	v_add_f32_e32 v163, v163, v164
	v_mul_f32_e32 v164, v35, v155
	v_mul_f32_e32 v165, v37, v157
	v_fmac_f32_e32 v164, v34, v151
	v_fmac_f32_e32 v165, v36, v153
	v_add_f32_e32 v163, 0, v163
	v_add_f32_e32 v164, v164, v165
	v_add_f32_e32 v163, v164, v163
	v_mul_f32_e32 v164, v39, v146
	v_mul_f32_e32 v165, v41, v148
	v_fmac_f32_e32 v164, v38, v0
	v_fmac_f32_e32 v165, v40, v144
	v_add_f32_e32 v164, v164, v165
	v_add_f32_e32 v163, v164, v163
	v_mul_f32_e32 v164, v47, v147
	v_mul_f32_e32 v165, v49, v149
	v_fmac_f32_e32 v164, v46, v143
	v_fmac_f32_e32 v165, v48, v145
	v_add_f32_e32 v164, v164, v165
	v_add_f32_e32 v163, v164, v163
	v_mul_f32_e32 v164, v27, v154
	v_mul_f32_e32 v165, v29, v156
	v_fmac_f32_e32 v164, v26, v150
	v_fmac_f32_e32 v165, v28, v152
	v_add_f32_e32 v164, v164, v165
	v_mul_f32_e32 v165, v19, v155
	v_mul_f32_e32 v166, v21, v157
	v_fmac_f32_e32 v165, v18, v151
	v_fmac_f32_e32 v166, v20, v153
	v_add_f32_e32 v164, 0, v164
	v_add_f32_e32 v165, v165, v166
	v_mul_f32_e32 v154, v11, v154
	v_add_f32_e32 v164, v165, v164
	v_mul_f32_e32 v165, v23, v146
	v_mul_f32_e32 v166, v25, v148
	v_fmac_f32_e32 v154, v10, v150
	v_mul_f32_e32 v150, v13, v156
	v_fmac_f32_e32 v165, v22, v0
	v_fmac_f32_e32 v166, v24, v144
	v_fmac_f32_e32 v150, v12, v152
	v_mul_f32_e32 v152, v3, v155
	v_mul_f32_e32 v146, v7, v146
	v_add_f32_e32 v165, v165, v166
	v_fmac_f32_e32 v152, v2, v151
	v_mul_f32_e32 v151, v5, v157
	v_fmac_f32_e32 v146, v6, v0
	v_mul_f32_e32 v0, v9, v148
	v_add_f32_e32 v164, v165, v164
	v_mul_f32_e32 v165, v31, v147
	v_add_f32_e32 v150, v154, v150
	v_fmac_f32_e32 v151, v4, v153
	v_fmac_f32_e32 v0, v8, v144
	v_mul_f32_e32 v144, v15, v147
	v_fmac_f32_e32 v165, v30, v143
	v_add_f32_e32 v150, 0, v150
	v_add_f32_e32 v151, v152, v151
	v_fmac_f32_e32 v144, v14, v143
	v_mul_f32_e32 v143, v17, v149
	v_add_f32_e32 v150, v151, v150
	v_add_f32_e32 v0, v146, v0
	v_fmac_f32_e32 v143, v16, v145
	v_add_f32_e32 v0, v0, v150
	v_add_f32_e32 v143, v144, v143
	v_add_f32_e32 v0, v143, v0
	v_cndmask_b32_e64 v143, v158, v162, s[0:1]
	ds_bpermute_b32 v143, v224, v143
	v_cndmask_b32_e64 v144, v162, v158, s[0:1]
	v_mul_f32_e32 v166, v33, v149
	v_fmac_f32_e32 v166, v32, v145
	v_add_f32_e32 v165, v165, v166
	s_waitcnt lgkmcnt(0)
; __device__ __forceinline__ float reduce8(const float (&d)[8], int lane) {
;     const bool h32 = (lane & 32) != 0, h16 = (lane & 16) != 0, h8 = (lane & 8) != 0;
;     float e[4];
; #pragma unroll
;     for (int i = 0; i < 4; ++i) { const float snd = h32 ? d[i] : d[4 + i], kp = h32 ? d[4 + i] : d[i]; e[i] = kp + __shfl_xor(snd, 32); }
;     float f[2];
; #pragma unroll
;     for (int i = 0; i < 2; ++i) { const float snd = h16 ? e[i] : e[2 + i], kp = h16 ? e[2 + i] : e[i]; f[i] = kp + __shfl_xor(snd, 16); }
;     const float snd = h8 ? f[0] : f[1], kp = h8 ? f[1] : f[0];
;     float g = kp + __shfl_xor(snd, 8);
;     g += __shfl_xor(g, 4); g += __shfl_xor(g, 2); g += __shfl_xor(g, 1);
;     return g;
; __device__ __forceinline__ void shw_tables(const Args& a, int t_lo, int t_hi, int gw, int ngw, int lane) {
;     ...
;                 const float tot = reduce8(d8, lane);
;                 if ((lane & 7) == 0) outp[(size_t)(lane >> 3) * nrows + r] = tot;
	v_add_f32_e32 v143, v144, v143
	v_cndmask_b32_e64 v144, v159, v163, s[0:1]
	ds_bpermute_b32 v144, v224, v144
	v_add_f32_e32 v164, v165, v164
	v_cndmask_b32_e64 v145, v163, v159, s[0:1]
	v_cndmask_b32_e64 v146, v164, v160, s[0:1]
	s_waitcnt lgkmcnt(0)
	v_add_f32_e32 v144, v145, v144
	v_cndmask_b32_e64 v145, v160, v164, s[0:1]
	ds_bpermute_b32 v145, v224, v145
	s_waitcnt lgkmcnt(0)
	v_add_f32_e32 v145, v146, v145
	v_cndmask_b32_e64 v146, v161, v0, s[0:1]
	ds_bpermute_b32 v146, v224, v146
	v_cndmask_b32_e64 v0, v0, v161, s[0:1]
	s_waitcnt lgkmcnt(0)
	v_add_f32_e32 v0, v0, v146
	v_cndmask_b32_e64 v146, v143, v145, s[2:3]
	v_cndmask_b32_e64 v143, v145, v143, s[2:3]
	ds_bpermute_b32 v145, v223, v146
	s_waitcnt lgkmcnt(0)
	v_add_f32_e32 v143, v143, v145
	v_cndmask_b32_e64 v145, v144, v0, s[2:3]
	v_cndmask_b32_e64 v0, v0, v144, s[2:3]
	ds_bpermute_b32 v144, v223, v145
	s_waitcnt lgkmcnt(0)
	v_add_f32_e32 v0, v0, v144
	v_cndmask_b32_e64 v144, v143, v0, s[4:5]
	v_cndmask_b32_e64 v0, v0, v143, s[4:5]
	ds_bpermute_b32 v143, v222, v144
	s_waitcnt lgkmcnt(0)
	v_add_f32_e32 v0, v0, v143
	ds_bpermute_b32 v143, v221, v0
	s_waitcnt lgkmcnt(0)
	v_add_f32_e32 v0, v0, v143
	ds_bpermute_b32 v143, v220, v0
	s_waitcnt lgkmcnt(0)
	v_add_f32_e32 v0, v0, v143
	ds_bpermute_b32 v143, v219, v0
	s_and_saveexec_b64 s[30:31], s[6:7]
	s_cbranch_execz .LBB0_42
	s_waitcnt lgkmcnt(0)
	v_add_f32_e32 v0, v0, v143
	global_store_dword v[138:139], v0, off
	s_branch .LBB0_42
